# gla_pass2: dropped conservative in-loop vmcnt waits guarding loop-invariant norm_g registers (drained once before the loop)
# baseline (speedup 1.0000x reference)
; #define GLA_WFRAG(h_) do { u32x4 w_ = (u32x4){0u, 0u, 0u, 0u}; if (fq < 2) { const float* wp_ = a.in[13] + (size_t)(l * 16 + 8 * fq) * 256 + (h_) * 64 + 16 * wq + fr; \
;         w_.x = pk2(wp_[0], wp_[256]); w_.y = pk2(wp_[512], wp_[768]); w_.z = pk2(wp_[1024], wp_[1280]); w_.w = pk2(wp_[1536], wp_[1792]); } wfr = __builtin_bit_cast(bf16x8, w_); } while (0)
; template <int PASS>
; __device__ __forceinline__ void gla_pass(CArgs& a, LAS unsigned char* lds, int l, int panel) {
;     ...
;     float* Sg = (float*)(ws + WS_GLAS) + ((size_t)panel * 4) * 8192;
;     bf16x8 wfr = (bf16x8){0, 0, 0, 0, 0, 0, 0, 0};
;     ...
;     f32x4 ngv[4];
; #pragma unroll
;     for (int k = 0; k < 4; ++k) ngv[k] = (PASS == 2) ? *(const f32x4*)(a.in[15] + l * 128 + 16 * (wh * 4 + k) + 4 * fq) : (f32x4){0.f, 0.f, 0.f, 0.f};
;     GLA_WFRAG(0);
;     GLA_XTILE(pgz[0], pgz[1]);
;     __syncthreads();
; #pragma unroll 1
;     for (int it = 0; it < 16; ++it) {
.LBB0_372:
	s_andn2_saveexec_b64 s[8:9], s[10:11]
	v_mov_b32_e32 v42, v1
	v_mov_b32_e32 v43, v1
	v_mov_b32_e32 v44, v1
	v_mov_b32_e32 v45, v1
	s_or_b64 exec, exec, s[8:9]
	s_movk_i32 s4, 0xa00
	v_lshlrev_b32_e32 v13, 2, v13
	v_add3_u32 v146, v5, v14, s4
	s_waitcnt vmcnt(32)
	v_mfma_f32_16x16x32_bf16 v[14:17], v[42:45], v[22:25], 0
	v_mul_lo_u32 v5, v3, s72
	v_or_b32_e32 v74, v13, v2
	v_add_lshl_u32 v5, v74, v5, 2
	v_mfma_f32_16x16x32_bf16 v[70:73], v[42:45], v[18:21], 0
	v_add_u32_e32 v147, s92, v5
	v_add_u32_e32 v5, 0x1100, v5
	s_movk_i32 s8, 0x90
	s_nop 0
	ds_write_b128 v147, v[14:17]
	v_add_u32_e32 v148, s92, v5
	v_add_u32_e32 v17, 0, v0
	v_add_u32_e32 v0, s1, v7
	v_mul_lo_u32 v7, v8, s74
	v_mul_lo_u32 v3, v3, s8
	ds_write_b128 v148, v[70:73]
	v_add_lshl_u32 v73, v7, v87, 2
	v_mul_lo_u32 v7, v9, s72
	v_add_u32_e32 v82, 0, v3
	v_or_b32_e32 v3, v13, v144
	v_or_b32_e32 v168, 16, v144
	v_add_lshl_u32 v169, v7, v87, 2
	v_or_b32_e32 v7, 2, v3
	s_add_u32 s10, s26, 0x140000
	v_or_b32_e32 v151, v13, v6
	v_lshl_add_u32 v154, v10, 2, s67
	v_add_u32_e32 v155, s67, v4
	v_cmp_gt_i32_e64 s[64:65], v3, v145
	v_cmp_lt_i32_e64 s[66:67], v3, v145
	v_cmp_gt_i32_e64 s[68:69], v7, v145
	v_or_b32_e32 v7, 3, v3
	v_lshlrev_b32_e32 v83, 1, v3
	v_or_b32_e32 v3, v168, v86
	s_addc_u32 s11, s27, 0
	v_mul_lo_u32 v163, v151, s8
	v_mul_lo_u32 v3, v3, s8
	s_add_u32 s4, s42, s70
	v_add_u32_e32 v166, 0x1320, v163
	v_add_u32_e32 v84, 0, v3
	v_or_b32_e32 v3, v168, v13
	s_addc_u32 s5, s43, s71
	v_add_u32_e32 v158, s73, v4
	v_or_b32_e32 v6, v6, v86
	s_waitcnt lgkmcnt(0)
	v_lshl_add_u64 v[4:5], v[0:1], 2, s[48:49]
	v_add_u32_e32 v0, 0, v166
	v_cmp_gt_i32_e64 s[70:71], v7, v145
	v_or_b32_e32 v7, 2, v3
	s_waitcnt vmcnt(0)
	s_barrier
	s_load_dwordx2 s[38:39], s[38:39], 0x70
	v_lshl_add_u32 v160, v145, 2, s73
	v_cmp_gt_i32_e64 s[72:73], v3, v145
	v_cmp_lt_i32_e64 s[74:75], v3, v145
	v_cmp_gt_i32_e64 s[76:77], v7, v145
	v_or_b32_e32 v7, 3, v3
	v_lshlrev_b32_e32 v85, 1, v3
	v_mul_lo_u32 v3, v6, s8
	v_add_u32_e32 v139, 0x7e0, v0
	v_lshlrev_b32_e32 v0, 2, v2
	v_readlane_b32 s9, v248, 28
	v_lshlrev_b32_e32 v152, 1, v145
	s_movk_i32 s18, 0x8e
	s_movk_i32 s1, 0x480
	v_add_u32_e32 v136, 0, v3
	v_lshl_add_u64 v[2:3], v[4:5], 0, v[0:1]
	v_lshlrev_b32_e32 v0, 2, v86
	v_lshl_add_u32 v16, v11, 2, s9
	v_or_b32_e32 v150, s60, v87
	v_add_u32_e32 v153, 0, v152
	v_mad_u32_u24 v156, v87, s18, v17
	v_lshlrev_b32_e32 v157, 4, v8
	v_cmp_gt_u32_e64 s[42:43], 64, v10
	v_cmp_lt_u32_e64 s[44:45], 1, v12
	v_lshlrev_b32_e32 v71, 3, v145
	v_lshl_or_b32 v94, v151, 6, v145
	v_or_b32_e32 v164, 16, v151
	v_or_b32_e32 v165, 32, v151
	v_or_b32_e32 v167, 48, v151
	v_cmp_lt_i32_e64 s[48:49], 0, v8
	v_cmp_lt_i32_e64 s[50:51], 1, v8
	v_cmp_lt_i32_e64 s[52:53], 2, v8
	v_cmp_lt_i32_e64 s[54:55], 3, v8
	v_cmp_lt_i32_e64 s[56:57], 4, v8
	v_cmp_lt_i32_e64 s[58:59], 5, v8
	v_cmp_lt_i32_e64 s[60:61], 6, v8
	v_cmp_lt_i32_e64 s[62:63], 7, v8
	v_mul_lo_u32 v80, v8, s1
	v_mul_lo_u32 v81, v9, s8
	v_cmp_gt_i32_e64 s[78:79], v7, v145
	v_add_u32_e32 v170, 0, v163
	v_lshl_add_u64 v[128:129], v[2:3], 0, v[0:1]
	v_mov_b32_e32 v2, v1
	v_mov_b32_e32 v3, v1
	v_mov_b32_e32 v4, v1
	v_mov_b32_e32 v5, v1
	v_mov_b32_e32 v6, v1
	v_mov_b32_e32 v7, v1
	v_mov_b32_e32 v8, v1
	v_mov_b32_e32 v9, v1
	v_mov_b32_e32 v10, v1
	v_mov_b32_e32 v11, v1
	v_mov_b32_e32 v12, v1
	v_mov_b32_e32 v13, v1
	v_mov_b32_e32 v14, v1
	v_mov_b32_e32 v15, v1
	s_add_u32 s20, s4, 0x4000000
	v_mad_u32_u24 v70, v87, s8, v156
	v_mad_u32_u24 v159, v145, s18, v153
	v_or_b32_e32 v98, 64, v94
	v_or_b32_e32 v100, 0x80, v94
	v_or_b32_e32 v102, 0xc0, v94
	v_lshl_or_b32 v104, v164, 6, v145
	v_or_b32_e32 v106, 0x440, v94
	v_add_u32_e32 v72, 0x990, v163
	v_or_b32_e32 v108, 0x480, v94
	v_or_b32_e32 v110, 0x4c0, v94
	v_lshl_or_b32 v112, v165, 6, v145
	v_or_b32_e32 v114, 0x840, v94
	v_or_b32_e32 v116, 0x880, v94
	v_or_b32_e32 v118, 0x8c0, v94
	v_lshl_or_b32 v120, v167, 6, v145
	v_or_b32_e32 v122, 0xc40, v94
	v_or_b32_e32 v124, 0xc80, v94
	v_or_b32_e32 v126, 0xcc0, v94
	v_add_u32_e32 v74, 0x110, v169
	v_add_u32_e32 v75, 0x220, v169
	v_add_u32_e32 v76, 0x330, v169
	v_add_u32_e32 v77, 0x440, v169
	v_add_u32_e32 v78, 0x550, v169
	v_add_u32_e32 v79, 0x660, v169
	v_add_u32_e32 v137, 0x900, v170
	v_add_u32_e32 v138, 0x1200, v170
	v_mov_b32_e32 v0, v1
	v_add_u32_e32 v172, v17, v80
	v_add_u32_e32 v173, v17, v81
	v_add_u32_e32 v180, v16, v71
	v_mov_b64_e32 v[16:17], v[14:15]
	v_or_b32_e32 v149, 0x100, v87
	s_addc_u32 s21, s5, 0
	s_mov_b32 s4, 1
	s_mov_b32 s5, 64
	v_cmp_gt_u32_e64 s[46:47], 16, v87
	v_add_u32_e32 v161, s9, v71
	v_lshlrev_b32_e32 v162, 11, v145
	v_ashrrev_i32_e32 v95, 31, v94
	v_ashrrev_i32_e32 v99, 31, v98
	v_ashrrev_i32_e32 v101, 31, v100
	v_ashrrev_i32_e32 v103, 31, v102
	v_ashrrev_i32_e32 v105, 31, v104
	v_ashrrev_i32_e32 v107, 31, v106
	v_ashrrev_i32_e32 v109, 31, v108
	v_ashrrev_i32_e32 v111, 31, v110
	v_ashrrev_i32_e32 v113, 31, v112
	v_ashrrev_i32_e32 v115, 31, v114
	v_ashrrev_i32_e32 v117, 31, v116
	v_ashrrev_i32_e32 v119, 31, v118
	v_ashrrev_i32_e32 v121, 31, v120
	v_ashrrev_i32_e32 v123, 31, v122
	v_ashrrev_i32_e32 v125, 31, v124
	v_ashrrev_i32_e32 v127, 31, v126
	v_mov_b32_e32 v174, 0
	v_add_u32_e32 v171, v153, v72
	v_add_u32_e32 v175, v70, v157
	v_add_u32_e32 v176, v82, v88
	v_add_u32_e32 v177, v159, v83
	v_add_u32_e32 v178, v84, v88
	v_add_u32_e32 v179, v159, v85
	v_add_u32_e32 v181, v137, v152
	v_add_u32_e32 v182, v138, v152
	v_add_u32_e32 v183, v139, v152
	v_add_u32_e32 v184, s92, v73
	v_add_u32_e32 v185, s92, v74
	v_add_u32_e32 v186, s92, v75
	v_add_u32_e32 v187, s92, v76
	v_add_u32_e32 v188, s92, v77
	v_add_u32_e32 v190, s92, v78
	v_add_u32_e32 v192, s92, v79
	v_add_u32_e32 v193, v136, v88
	v_mov_b64_e32 v[14:15], v[12:13]
	v_mov_b64_e32 v[12:13], v[10:11]
	v_mov_b64_e32 v[10:11], v[8:9]
	v_mov_b64_e32 v[8:9], v[6:7]
	v_mov_b64_e32 v[6:7], v[4:5]
	v_mov_b64_e32 v[4:5], v[2:3]
	v_mov_b64_e32 v[2:3], v[0:1]
	s_branch .LBB0_376

; #define LAS __attribute__((address_space(3)))
; __device__ __forceinline__ unsigned pk2(float lo, float hi) { unsigned r; asm("v_cvt_pk_bf16_f32 %0, %1, %2" : "=v"(r) : "v"(lo), "v"(hi)); return r; }
; __device__ __forceinline__ float bflo(unsigned w) { return __uint_as_float(w << 16); }
; __device__ __forceinline__ float bfhi(unsigned w) { return __uint_as_float(w & 0xffff0000u); }
; template <int PASS>
; __device__ __forceinline__ void gla_pass(CArgs& a, LAS unsigned char* lds, int l, int panel) {
;     ...
;         __syncthreads();
;         if (PASS == 2) {
;             const int i = 16 * wq + fr;
;             const float rs = rsqrtf((SS[i * 2] + SS[i * 2 + 1]) * (1.f / 128.f) + 1e-6f);
; #pragma unroll
;             for (int k = 0; k < 4; ++k) {
;                 const int e0 = 16 * (wh * 4 + k) + 4 * fq;
;                 const f32x4 ng = ngv[k];
;                 const u32x2 rv = rvv[k];
;                 const float r0 = bflo(rv.x), r1 = bfhi(rv.x), r2 = bflo(rv.y), r3 = bfhi(rv.y);
;                 u32x2 w; w.x = pk2(o[k][0] * rs * ng[0] * r0 * sigmoidf_(r0), o[k][1] * rs * ng[1] * r1 * sigmoidf_(r1));
;                 w.y = pk2(o[k][2] * rs * ng[2] * r2 * sigmoidf_(r2), o[k][3] * rs * ng[3] * r3 * sigmoidf_(r3));
;                 *(u32x2*)(MIX + (size_t)(row0 + i) * 2048 + (256 + h * 128 + e0) * 2) = w;
;                 { const unsigned s01 = pk2(st[k][0], st[k][1]), s23 = pk2(st[k][2], st[k][3]);
;                   *(LAS bf16_t*)(lds + GL_ST + (e0 + 0) * GRS + (16 * wq + fr) * 2) = (bf16_t)(s01 & 0xffffu); *(LAS bf16_t*)(lds + GL_ST + (e0 + 1) * GRS + (16 * wq + fr) * 2) = (bf16_t)(s01 >> 16);
;                   *(LAS bf16_t*)(lds + GL_ST + (e0 + 2) * GRS + (16 * wq + fr) * 2) = (bf16_t)(s23 & 0xffffu); *(LAS bf16_t*)(lds + GL_ST + (e0 + 3) * GRS + (16 * wq + fr) * 2) = (bf16_t)(s23 >> 16); }
;             }
;         }
;         if (c == 3) {
;             if (PASS == 1) {
; #pragma unroll
;                 for (int k = 0; k < 4; ++k)
; #pragma unroll
;                     for (int r = 0; r < 4; ++r) Sg[(16 * (wh * 4 + k) + 4 * fq + r) * 64 + 16 * wq + fr] = st[k][r];
;                 if (wh == 0 && fq == 0) ((float*)(ws + WS_GLAD))[((size_t)panel * 4 + h) * 64 + 16 * wq + fr] = dprod;
;             }
;             __syncthreads();
;         }
.LBB0_400:
	s_waitcnt lgkmcnt(0)
	s_barrier
	ds_read_b64 v[62:63], v161
	s_mov_b32 s1, 0x800000
	v_and_b32_e32 v65, 0xffff0000, v134
	v_lshlrev_b32_e32 v66, 16, v135
	v_and_b32_e32 v67, 0xffff0000, v135
	s_waitcnt lgkmcnt(0)
	v_add_f32_e32 v0, v62, v63
	v_fmamk_f32 v0, v0, 0x3c000000, v230
	v_cmp_gt_f32_e32 vcc, s1, v0
	v_mul_f32_e32 v62, 0x4b800000, v0
	s_lshl_b32 s8, s19, 7
	v_cndmask_b32_e32 v0, v0, v62, vcc
	v_rsq_f32_e32 v0, v0
	s_addk_i32 s8, 0x100
	s_cmp_lg_u32 s18, 3
	v_mul_f32_e32 v62, 0x45800000, v0
	v_cndmask_b32_e32 v64, v0, v62, vcc
	v_lshl_or_b32 v0, s18, 17, v162
	v_mul_f32_e32 v58, v58, v64
	v_lshl_add_u64 v[62:63], s[10:11], 0, v[0:1]
	v_lshlrev_b32_e32 v0, 16, v134
	s_nop 0
	v_mul_f32_e32 v58, v26, v58
	v_mul_f32_e32 v58, v58, v0
	v_mul_f32_e32 v0, 0xbfb8aa3b, v0
	v_exp_f32_e32 v0, v0
	v_mul_f32_e32 v54, v54, v64
	s_nop 0
	v_mul_f32_e32 v54, v30, v54
	v_mul_f32_e32 v50, v50, v64
	v_add_f32_e32 v0, 1.0, v0
	v_rcp_f32_e32 v0, v0
	s_nop 0
	v_mul_f32_e32 v50, v34, v50
	v_mul_f32_e32 v46, v46, v64
	s_nop 0
	v_mul_f32_e32 v46, v38, v46
	v_mul_f32_e32 v0, v0, v58
	v_mul_f32_e32 v58, v59, v64
	v_mul_f32_e32 v59, 0xbfb8aa3b, v65
	v_exp_f32_e32 v59, v59
	v_mul_f32_e32 v58, v27, v58
	v_mul_f32_e32 v58, v58, v65
	v_add_f32_e32 v59, 1.0, v59
	v_rcp_f32_e32 v59, v59
	s_nop 0
	v_mul_f32_e32 v58, v59, v58
	v_mul_f32_e32 v59, 0xbfb8aa3b, v66
	v_exp_f32_e32 v59, v59
	v_cvt_pk_bf16_f32 v58, v0, v58
	v_mul_f32_e32 v0, v60, v64
	v_mul_f32_e32 v60, 0xbfb8aa3b, v67
	v_exp_f32_e32 v60, v60
	v_add_f32_e32 v59, 1.0, v59
	v_rcp_f32_e32 v59, v59
	v_mul_f32_e32 v0, v28, v0
	v_add_f32_e32 v60, 1.0, v60
	v_mul_f32_e32 v0, v0, v66
	v_rcp_f32_e32 v60, v60
	v_mul_f32_e32 v0, v59, v0
	v_mul_f32_e32 v59, v61, v64
	v_mul_f32_e32 v59, v29, v59
	v_mul_f32_e32 v59, v59, v67
	v_mul_f32_e32 v59, v60, v59
	v_add_lshl_u32 v60, s8, v151, 1
	v_ashrrev_i32_e32 v61, 31, v60
	v_cvt_pk_bf16_f32 v59, v0, v59
	v_lshl_add_u64 v[60:61], v[62:63], 0, v[60:61]
	global_store_dwordx2 v[60:61], v[58:59], off
	v_cvt_pk_bf16_f32 v0, v2, v3
	v_add_u32_e32 v59, v170, v152
	v_cvt_pk_bf16_f32 v58, v4, v5
	ds_write_b16 v59, v0 offset:55296
	ds_write_b16_d16_hi v59, v0 offset:55440
	ds_write_b16 v59, v58 offset:55584
	ds_write_b16_d16_hi v59, v58 offset:55728
	v_lshlrev_b32_e32 v0, 16, v132
	v_mul_f32_e32 v54, v54, v0
	v_mul_f32_e32 v0, 0xbfb8aa3b, v0
	v_exp_f32_e32 v0, v0
	v_and_b32_e32 v58, 0xffff0000, v132
	v_lshlrev_b32_e32 v59, 16, v133
	v_and_b32_e32 v60, 0xffff0000, v133
	v_add_f32_e32 v0, 1.0, v0
	v_rcp_f32_e32 v0, v0
	s_nop 0
	v_mul_f32_e32 v0, v0, v54
	v_mul_f32_e32 v54, v55, v64
	v_mul_f32_e32 v55, 0xbfb8aa3b, v58
	v_exp_f32_e32 v55, v55
	v_mul_f32_e32 v54, v31, v54
	v_mul_f32_e32 v54, v54, v58
	v_add_f32_e32 v55, 1.0, v55
	v_rcp_f32_e32 v55, v55
	s_nop 0
	v_mul_f32_e32 v54, v55, v54
	v_mul_f32_e32 v55, 0xbfb8aa3b, v59
	v_exp_f32_e32 v55, v55
	v_cvt_pk_bf16_f32 v54, v0, v54
	v_mul_f32_e32 v0, v56, v64
	v_mul_f32_e32 v56, 0xbfb8aa3b, v60
	v_exp_f32_e32 v56, v56
	v_add_f32_e32 v55, 1.0, v55
	v_rcp_f32_e32 v55, v55
	v_mul_f32_e32 v0, v32, v0
	v_add_f32_e32 v56, 1.0, v56
	v_mul_f32_e32 v0, v0, v59
	v_rcp_f32_e32 v56, v56
	v_mul_f32_e32 v0, v55, v0
	v_mul_f32_e32 v55, v57, v64
	v_mul_f32_e32 v55, v33, v55
	v_mul_f32_e32 v55, v55, v60
	v_mul_f32_e32 v55, v56, v55
	v_add_lshl_u32 v56, s8, v164, 1
	v_ashrrev_i32_e32 v57, 31, v56
	v_cvt_pk_bf16_f32 v55, v0, v55
	v_lshl_add_u64 v[56:57], v[62:63], 0, v[56:57]
	v_cvt_pk_bf16_f32 v0, v6, v7
	global_store_dwordx2 v[56:57], v[54:55], off
	v_cvt_pk_bf16_f32 v54, v8, v9
	ds_write_b16 v181, v0 offset:55296
	ds_write_b16_d16_hi v181, v0 offset:55440
	ds_write_b16 v181, v54 offset:55584
	ds_write_b16_d16_hi v181, v54 offset:55728
	v_lshlrev_b32_e32 v0, 16, v130
	v_mul_f32_e32 v50, v50, v0
	v_mul_f32_e32 v0, 0xbfb8aa3b, v0
	v_exp_f32_e32 v0, v0
	v_and_b32_e32 v54, 0xffff0000, v130
	v_lshlrev_b32_e32 v55, 16, v131
	v_and_b32_e32 v56, 0xffff0000, v131
	v_add_f32_e32 v0, 1.0, v0
	v_rcp_f32_e32 v0, v0
	s_nop 0
	v_mul_f32_e32 v0, v0, v50
	v_mul_f32_e32 v50, v51, v64
	v_mul_f32_e32 v51, 0xbfb8aa3b, v54
	v_exp_f32_e32 v51, v51
	v_mul_f32_e32 v50, v35, v50
	v_mul_f32_e32 v50, v50, v54
	v_add_f32_e32 v51, 1.0, v51
	v_rcp_f32_e32 v51, v51
	s_nop 0
	v_mul_f32_e32 v50, v51, v50
	v_mul_f32_e32 v51, 0xbfb8aa3b, v55
	v_exp_f32_e32 v51, v51
	v_cvt_pk_bf16_f32 v50, v0, v50
	v_mul_f32_e32 v0, v52, v64
	v_mul_f32_e32 v52, 0xbfb8aa3b, v56
	v_exp_f32_e32 v52, v52
	v_add_f32_e32 v51, 1.0, v51
	v_rcp_f32_e32 v51, v51
	v_mul_f32_e32 v0, v36, v0
	v_add_f32_e32 v52, 1.0, v52
	v_mul_f32_e32 v0, v0, v55
	v_rcp_f32_e32 v52, v52
	v_mul_f32_e32 v0, v51, v0
	v_mul_f32_e32 v51, v53, v64
	v_mul_f32_e32 v51, v37, v51
	v_mul_f32_e32 v51, v51, v56
	v_mul_f32_e32 v51, v52, v51
	v_add_lshl_u32 v52, s8, v165, 1
	v_ashrrev_i32_e32 v53, 31, v52
	v_cvt_pk_bf16_f32 v51, v0, v51
	v_lshl_add_u64 v[52:53], v[62:63], 0, v[52:53]
	v_cvt_pk_bf16_f32 v0, v10, v11
	global_store_dwordx2 v[52:53], v[50:51], off
	v_cvt_pk_bf16_f32 v50, v12, v13
	ds_write_b16 v182, v0 offset:55296
	ds_write_b16_d16_hi v182, v0 offset:55440
	ds_write_b16 v182, v50 offset:55584
	ds_write_b16_d16_hi v182, v50 offset:55728
	v_lshlrev_b32_e32 v0, 16, v96
	v_mul_f32_e32 v46, v46, v0
	v_mul_f32_e32 v0, 0xbfb8aa3b, v0
	v_exp_f32_e32 v0, v0
	v_and_b32_e32 v50, 0xffff0000, v96
	v_lshlrev_b32_e32 v51, 16, v97
	v_and_b32_e32 v52, 0xffff0000, v97
	v_add_f32_e32 v0, 1.0, v0
	v_rcp_f32_e32 v0, v0
	s_nop 0
	v_mul_f32_e32 v0, v0, v46
	v_mul_f32_e32 v46, v47, v64
	v_mul_f32_e32 v47, 0xbfb8aa3b, v50
	v_exp_f32_e32 v47, v47
	v_mul_f32_e32 v46, v39, v46
	v_mul_f32_e32 v46, v46, v50
	v_add_f32_e32 v47, 1.0, v47
	v_rcp_f32_e32 v47, v47
	s_nop 0
	v_mul_f32_e32 v46, v47, v46
	v_mul_f32_e32 v47, 0xbfb8aa3b, v51
	v_exp_f32_e32 v47, v47
	v_cvt_pk_bf16_f32 v46, v0, v46
	v_mul_f32_e32 v0, v48, v64
	v_mul_f32_e32 v48, 0xbfb8aa3b, v52
	v_exp_f32_e32 v48, v48
	v_add_f32_e32 v47, 1.0, v47
	v_rcp_f32_e32 v47, v47
	v_mul_f32_e32 v0, v40, v0
	v_add_f32_e32 v48, 1.0, v48
	v_mul_f32_e32 v0, v0, v51
	v_rcp_f32_e32 v48, v48
	v_mul_f32_e32 v0, v47, v0
	v_mul_f32_e32 v47, v49, v64
	v_mul_f32_e32 v47, v41, v47
	v_mul_f32_e32 v47, v47, v52
	v_mul_f32_e32 v47, v48, v47
	v_add_lshl_u32 v48, s8, v167, 1
	v_ashrrev_i32_e32 v49, 31, v48
	v_cvt_pk_bf16_f32 v47, v0, v47
	v_lshl_add_u64 v[48:49], v[62:63], 0, v[48:49]
	v_cvt_pk_bf16_f32 v0, v14, v15
	global_store_dwordx2 v[48:49], v[46:47], off
	v_cvt_pk_bf16_f32 v46, v16, v17
	ds_write_b16 v183, v0 offset:55296
	ds_write_b16_d16_hi v183, v0 offset:55440
	ds_write_b16 v183, v46 offset:55584
	ds_write_b16_d16_hi v183, v46 offset:55728
	s_cbranch_scc1 .LBB0_375
	s_waitcnt lgkmcnt(0)
	s_barrier
	s_branch .LBB0_375
